# A/B: s_setprio brackets around attention-phase MFMA bursts removed again (GEMM static raise kept)
# baseline (speedup 1.0000x reference)
.Lsw_p1:
	v_lshl_add_u32 v114, s82, 2, v145
	ds_read2_b32 v[82:83], v114 offset0:127 offset1:128
	ds_read2_b32 v[84:85], v114 offset0:129 offset1:130
	ds_read2_b32 v[86:87], v114 offset0:143 offset1:144
	ds_read2_b32 v[88:89], v114 offset0:145 offset1:146
	s_waitcnt lgkmcnt(4)
	v_mfma_f32_16x16x32_bf16 v[98:101], v[70:73], v[10:13], 0
	v_mfma_f32_16x16x32_bf16 v[102:105], v[74:77], v[10:13], 0
	v_mfma_f32_16x16x32_bf16 v[106:109], v[62:65], v[10:13], 0
	v_mfma_f32_16x16x32_bf16 v[110:113], v[54:57], v[10:13], 0
	ds_read2_b32 v[90:91], v114 offset0:159 offset1:160
	ds_read2_b32 v[92:93], v114 offset0:161 offset1:162
	ds_read2_b32 v[94:95], v114 offset0:175 offset1:176
	ds_read2_b32 v[96:97], v114 offset0:177 offset1:178
	v_mfma_f32_16x16x32_bf16 v[98:101], v[78:81], v[14:17], v[98:101]
	v_mfma_f32_16x16x32_bf16 v[102:105], v[66:69], v[14:17], v[102:105]
	v_mfma_f32_16x16x32_bf16 v[106:109], v[58:61], v[14:17], v[106:109]
	v_mfma_f32_16x16x32_bf16 v[110:113], v[50:53], v[14:17], v[110:113]
	v_mfma_f32_16x16x32_bf16 v[70:73], v[70:73], v[2:5], 0
	v_mfma_f32_16x16x32_bf16 v[74:77], v[74:77], v[2:5], 0
	v_mfma_f32_16x16x32_bf16 v[62:65], v[62:65], v[2:5], 0
	v_mfma_f32_16x16x32_bf16 v[54:57], v[54:57], v[2:5], 0
	v_mfma_f32_16x16x32_bf16 v[70:73], v[78:81], v[6:9], v[70:73]
	v_mfma_f32_16x16x32_bf16 v[74:77], v[66:69], v[6:9], v[74:77]
	v_mfma_f32_16x16x32_bf16 v[62:65], v[58:61], v[6:9], v[62:65]
	v_mfma_f32_16x16x32_bf16 v[54:57], v[50:53], v[6:9], v[54:57]
	s_waitcnt lgkmcnt(0)
	ds_read2_b32 v[78:79], v114 offset0:111 offset1:112
	ds_read2_b32 v[80:81], v114 offset0:113 offset1:114
	ds_read2_b32 v[66:67], v114 offset0:127 offset1:128
	ds_read2_b32 v[68:69], v114 offset0:129 offset1:130
	ds_read2_b32 v[58:59], v114 offset0:143 offset1:144
	ds_read2_b32 v[60:61], v114 offset0:145 offset1:146
	ds_read2_b32 v[50:51], v114 offset0:159 offset1:160
	ds_read2_b32 v[52:53], v114 offset0:161 offset1:162
	v_pk_fma_f32 v[70:71], v[70:71], s[36:37], v[82:83] op_sel_hi:[1,0,1]
	v_pk_fma_f32 v[72:73], v[72:73], s[36:37], v[84:85] op_sel_hi:[1,0,1]
	v_pk_fma_f32 v[74:75], v[74:75], s[36:37], v[86:87] op_sel_hi:[1,0,1]
	v_pk_fma_f32 v[76:77], v[76:77], s[36:37], v[88:89] op_sel_hi:[1,0,1]
	v_pk_fma_f32 v[62:63], v[62:63], s[36:37], v[90:91] op_sel_hi:[1,0,1]
	v_pk_fma_f32 v[64:65], v[64:65], s[36:37], v[92:93] op_sel_hi:[1,0,1]
	v_pk_fma_f32 v[54:55], v[54:55], s[36:37], v[94:95] op_sel_hi:[1,0,1]
	v_pk_fma_f32 v[56:57], v[56:57], s[36:37], v[96:97] op_sel_hi:[1,0,1]
	s_waitcnt lgkmcnt(0)
	v_pk_fma_f32 v[98:99], v[98:99], s[36:37], v[78:79] op_sel_hi:[1,0,1]
	v_pk_fma_f32 v[100:101], v[100:101], s[36:37], v[80:81] op_sel_hi:[1,0,1]
	v_pk_fma_f32 v[102:103], v[102:103], s[36:37], v[66:67] op_sel_hi:[1,0,1]
	v_pk_fma_f32 v[104:105], v[104:105], s[36:37], v[68:69] op_sel_hi:[1,0,1]
	v_pk_fma_f32 v[106:107], v[106:107], s[36:37], v[58:59] op_sel_hi:[1,0,1]
	v_pk_fma_f32 v[108:109], v[108:109], s[36:37], v[60:61] op_sel_hi:[1,0,1]
	v_pk_fma_f32 v[110:111], v[110:111], s[36:37], v[50:51] op_sel_hi:[1,0,1]
	v_pk_fma_f32 v[112:113], v[112:113], s[36:37], v[52:53] op_sel_hi:[1,0,1]
	v_max3_f32 v116, v70, v71, v72
	v_max3_f32 v169, v98, v99, v100
	v_max3_f32 v116, v116, v73, v74
	v_max3_f32 v169, v169, v101, v102
	v_max3_f32 v116, v116, v75, v76
	v_max3_f32 v169, v169, v103, v104
	v_max3_f32 v116, v116, v77, v62
	v_max3_f32 v169, v169, v105, v106
	v_max3_f32 v116, v116, v63, v64
	v_max3_f32 v169, v169, v107, v108
	v_max3_f32 v116, v116, v65, v54
	v_max3_f32 v169, v169, v109, v110
	v_max3_f32 v116, v116, v55, v56
	v_max3_f32 v169, v169, v111, v112
	v_max3_f32 v116, v116, v57, s29
	v_max3_f32 v169, v169, v113, s29
	v_mov_b32_e32 v117, v116
	v_mov_b32_e32 v170, v169
	s_nop 0
	v_permlane16_swap_b32_e32 v116, v117
	v_permlane16_swap_b32_e32 v169, v170
	v_max_f32_e32 v116, v116, v117
	v_max_f32_e32 v169, v169, v170
	v_mov_b32_e32 v117, v116
	v_mov_b32_e32 v170, v169
	s_nop 0
	v_permlane32_swap_b32_e32 v116, v117
	v_permlane32_swap_b32_e32 v169, v170
	v_max_f32_e32 v116, v116, v117
	v_max_f32_e32 v169, v169, v170
	v_max_f32_e32 v121, v166, v116
	v_max_f32_e32 v175, v167, v169
	v_sub_f32_e32 v118, v166, v121
	v_sub_f32_e32 v172, v167, v175
	v_exp_f32_e32 v118, v118
	v_exp_f32_e32 v172, v172
	v_mov_b32_e32 v166, v121
	v_mov_b32_e32 v167, v175
	v_mov_b32_e32 v120, v121
	v_mov_b32_e32 v174, v175
	v_pk_mul_f32 v[46:47], v[46:47], v[118:119] op_sel_hi:[1,0]
	v_pk_mul_f32 v[30:31], v[30:31], v[172:173] op_sel_hi:[1,0]
	v_pk_mul_f32 v[48:49], v[48:49], v[118:119] op_sel_hi:[1,0]
	v_pk_mul_f32 v[32:33], v[32:33], v[172:173] op_sel_hi:[1,0]
	v_pk_mul_f32 v[42:43], v[42:43], v[118:119] op_sel_hi:[1,0]
	v_pk_mul_f32 v[26:27], v[26:27], v[172:173] op_sel_hi:[1,0]
	v_pk_mul_f32 v[44:45], v[44:45], v[118:119] op_sel_hi:[1,0]
	v_pk_mul_f32 v[28:29], v[28:29], v[172:173] op_sel_hi:[1,0]
	v_pk_mul_f32 v[38:39], v[38:39], v[118:119] op_sel_hi:[1,0]
	v_pk_mul_f32 v[22:23], v[22:23], v[172:173] op_sel_hi:[1,0]
	v_pk_mul_f32 v[40:41], v[40:41], v[118:119] op_sel_hi:[1,0]
	v_pk_mul_f32 v[24:25], v[24:25], v[172:173] op_sel_hi:[1,0]
	v_pk_mul_f32 v[34:35], v[34:35], v[118:119] op_sel_hi:[1,0]
	v_pk_mul_f32 v[18:19], v[18:19], v[172:173] op_sel_hi:[1,0]
	v_pk_mul_f32 v[36:37], v[36:37], v[118:119] op_sel_hi:[1,0]
	v_pk_mul_f32 v[20:21], v[20:21], v[172:173] op_sel_hi:[1,0]
	v_pk_add_f32 v[70:71], v[70:71], v[120:121] op_sel_hi:[1,0] neg_lo:[0,1] neg_hi:[0,1]
	v_pk_add_f32 v[98:99], v[98:99], v[174:175] op_sel_hi:[1,0] neg_lo:[0,1] neg_hi:[0,1]
	v_pk_add_f32 v[72:73], v[72:73], v[120:121] op_sel_hi:[1,0] neg_lo:[0,1] neg_hi:[0,1]
	v_pk_add_f32 v[100:101], v[100:101], v[174:175] op_sel_hi:[1,0] neg_lo:[0,1] neg_hi:[0,1]
	v_pk_add_f32 v[74:75], v[74:75], v[120:121] op_sel_hi:[1,0] neg_lo:[0,1] neg_hi:[0,1]
	v_pk_add_f32 v[102:103], v[102:103], v[174:175] op_sel_hi:[1,0] neg_lo:[0,1] neg_hi:[0,1]
	v_pk_add_f32 v[76:77], v[76:77], v[120:121] op_sel_hi:[1,0] neg_lo:[0,1] neg_hi:[0,1]
	v_pk_add_f32 v[104:105], v[104:105], v[174:175] op_sel_hi:[1,0] neg_lo:[0,1] neg_hi:[0,1]
	v_pk_add_f32 v[62:63], v[62:63], v[120:121] op_sel_hi:[1,0] neg_lo:[0,1] neg_hi:[0,1]
	v_pk_add_f32 v[106:107], v[106:107], v[174:175] op_sel_hi:[1,0] neg_lo:[0,1] neg_hi:[0,1]
	v_pk_add_f32 v[64:65], v[64:65], v[120:121] op_sel_hi:[1,0] neg_lo:[0,1] neg_hi:[0,1]
	v_pk_add_f32 v[108:109], v[108:109], v[174:175] op_sel_hi:[1,0] neg_lo:[0,1] neg_hi:[0,1]
	v_pk_add_f32 v[54:55], v[54:55], v[120:121] op_sel_hi:[1,0] neg_lo:[0,1] neg_hi:[0,1]
	v_pk_add_f32 v[110:111], v[110:111], v[174:175] op_sel_hi:[1,0] neg_lo:[0,1] neg_hi:[0,1]
	v_pk_add_f32 v[56:57], v[56:57], v[120:121] op_sel_hi:[1,0] neg_lo:[0,1] neg_hi:[0,1]
	v_pk_add_f32 v[112:113], v[112:113], v[174:175] op_sel_hi:[1,0] neg_lo:[0,1] neg_hi:[0,1]
	v_exp_f32_e32 v70, v70
	v_exp_f32_e32 v98, v98
	v_exp_f32_e32 v71, v71
	v_exp_f32_e32 v99, v99
	v_exp_f32_e32 v72, v72
	v_exp_f32_e32 v100, v100
	v_exp_f32_e32 v73, v73
	v_exp_f32_e32 v101, v101
	v_exp_f32_e32 v74, v74
	v_exp_f32_e32 v102, v102
	v_exp_f32_e32 v75, v75
	v_exp_f32_e32 v103, v103
	v_exp_f32_e32 v76, v76
	v_exp_f32_e32 v104, v104
	v_exp_f32_e32 v77, v77
	v_exp_f32_e32 v105, v105
	v_exp_f32_e32 v62, v62
	v_exp_f32_e32 v106, v106
	v_exp_f32_e32 v63, v63
	v_exp_f32_e32 v107, v107
	v_exp_f32_e32 v64, v64
	v_exp_f32_e32 v108, v108
	v_exp_f32_e32 v65, v65
	v_exp_f32_e32 v109, v109
	v_exp_f32_e32 v54, v54
	v_exp_f32_e32 v110, v110
	v_exp_f32_e32 v55, v55
	v_exp_f32_e32 v111, v111
	v_exp_f32_e32 v56, v56
	v_exp_f32_e32 v112, v112
	v_exp_f32_e32 v57, v57
	v_exp_f32_e32 v113, v113
	v_pk_add_f32 v[82:83], v[70:71], v[72:73]
	v_pk_add_f32 v[78:79], v[98:99], v[100:101]
	v_pk_add_f32 v[84:85], v[74:75], v[76:77]
	v_pk_add_f32 v[80:81], v[102:103], v[104:105]
	v_pk_add_f32 v[86:87], v[62:63], v[64:65]
	v_pk_add_f32 v[66:67], v[106:107], v[108:109]
	v_pk_add_f32 v[88:89], v[54:55], v[56:57]
	v_pk_add_f32 v[68:69], v[110:111], v[112:113]
	v_pk_add_f32 v[82:83], v[82:83], v[84:85]
	v_pk_add_f32 v[78:79], v[78:79], v[80:81]
	v_pk_add_f32 v[86:87], v[86:87], v[88:89]
	v_pk_add_f32 v[66:67], v[66:67], v[68:69]
	v_pk_add_f32 v[82:83], v[82:83], v[86:87]
	v_pk_add_f32 v[78:79], v[78:79], v[66:67]
	v_add_f32_e32 v82, v82, v83
	v_add_f32_e32 v78, v78, v79
	v_fma_f32 v158, v158, v118, v82
	v_fma_f32 v159, v159, v172, v78
	v_cvt_pk_bf16_f32 v77, v76, v77
	v_cvt_pk_bf16_f32 v105, v104, v105
	v_cvt_pk_bf16_f32 v76, v74, v75
	v_cvt_pk_bf16_f32 v104, v102, v103
	v_cvt_pk_bf16_f32 v75, v72, v73
	v_cvt_pk_bf16_f32 v103, v100, v101
	v_cvt_pk_bf16_f32 v74, v70, v71
	v_cvt_pk_bf16_f32 v102, v98, v99
	v_cvt_pk_bf16_f32 v62, v62, v63
	v_cvt_pk_bf16_f32 v106, v106, v107
	v_cvt_pk_bf16_f32 v63, v64, v65
	v_cvt_pk_bf16_f32 v107, v108, v109
	v_cvt_pk_bf16_f32 v64, v54, v55
	v_cvt_pk_bf16_f32 v108, v110, v111
	v_cvt_pk_bf16_f32 v65, v56, v57
	v_cvt_pk_bf16_f32 v109, v112, v113

.Lnw_p1:
	v_lshl_add_u32 v114, s25, 2, v145
	v_add_u32_e32 v115, 0xffc, v114
	v_add_u32_e32 v168, 0xfbc, v114
	ds_read2_b32 v[82:83], v115 offset1:1
	ds_read2_b32 v[84:85], v115 offset0:2 offset1:3
	ds_read2_b32 v[86:87], v115 offset0:16 offset1:17
	ds_read2_b32 v[88:89], v115 offset0:18 offset1:19
	s_waitcnt lgkmcnt(4)
	v_mfma_f32_16x16x32_bf16 v[98:101], v[78:81], v[10:13], 0
	v_mfma_f32_16x16x32_bf16 v[102:105], v[70:73], v[10:13], 0
	v_mfma_f32_16x16x32_bf16 v[106:109], v[62:65], v[10:13], 0
	v_mfma_f32_16x16x32_bf16 v[110:113], v[54:57], v[10:13], 0
	ds_read2_b32 v[90:91], v115 offset0:32 offset1:33
	ds_read2_b32 v[92:93], v115 offset0:34 offset1:35
	ds_read2_b32 v[94:95], v115 offset0:48 offset1:49
	ds_read2_b32 v[96:97], v115 offset0:50 offset1:51
	v_mfma_f32_16x16x32_bf16 v[98:101], v[74:77], v[14:17], v[98:101]
	v_mfma_f32_16x16x32_bf16 v[102:105], v[66:69], v[14:17], v[102:105]
	v_mfma_f32_16x16x32_bf16 v[106:109], v[58:61], v[14:17], v[106:109]
	v_mfma_f32_16x16x32_bf16 v[110:113], v[50:53], v[14:17], v[110:113]
	v_mfma_f32_16x16x32_bf16 v[78:81], v[78:81], v[2:5], 0
	v_mfma_f32_16x16x32_bf16 v[70:73], v[70:73], v[2:5], 0
	v_mfma_f32_16x16x32_bf16 v[62:65], v[62:65], v[2:5], 0
	v_mfma_f32_16x16x32_bf16 v[54:57], v[54:57], v[2:5], 0
	v_mfma_f32_16x16x32_bf16 v[78:81], v[74:77], v[6:9], v[78:81]
	v_mfma_f32_16x16x32_bf16 v[70:73], v[66:69], v[6:9], v[70:73]
	v_mfma_f32_16x16x32_bf16 v[62:65], v[58:61], v[6:9], v[62:65]
	v_mfma_f32_16x16x32_bf16 v[54:57], v[50:53], v[6:9], v[54:57]
	s_waitcnt lgkmcnt(0)
	ds_read2_b32 v[74:75], v168 offset1:1
	ds_read2_b32 v[76:77], v168 offset0:2 offset1:3
	ds_read2_b32 v[66:67], v168 offset0:16 offset1:17
	ds_read2_b32 v[68:69], v168 offset0:18 offset1:19
	ds_read2_b32 v[58:59], v168 offset0:32 offset1:33
	ds_read2_b32 v[60:61], v168 offset0:34 offset1:35
	ds_read2_b32 v[50:51], v168 offset0:48 offset1:49
	ds_read2_b32 v[52:53], v168 offset0:50 offset1:51
	v_pk_fma_f32 v[78:79], v[78:79], s[36:37], v[82:83] op_sel_hi:[1,0,1]
	v_pk_fma_f32 v[80:81], v[80:81], s[36:37], v[84:85] op_sel_hi:[1,0,1]
	v_pk_fma_f32 v[70:71], v[70:71], s[36:37], v[86:87] op_sel_hi:[1,0,1]
	v_pk_fma_f32 v[72:73], v[72:73], s[36:37], v[88:89] op_sel_hi:[1,0,1]
	v_pk_fma_f32 v[62:63], v[62:63], s[36:37], v[90:91] op_sel_hi:[1,0,1]
	v_pk_fma_f32 v[64:65], v[64:65], s[36:37], v[92:93] op_sel_hi:[1,0,1]
	v_pk_fma_f32 v[54:55], v[54:55], s[36:37], v[94:95] op_sel_hi:[1,0,1]
	v_pk_fma_f32 v[56:57], v[56:57], s[36:37], v[96:97] op_sel_hi:[1,0,1]
	s_waitcnt lgkmcnt(0)
	v_pk_fma_f32 v[98:99], v[98:99], s[36:37], v[74:75] op_sel_hi:[1,0,1]
	v_pk_fma_f32 v[100:101], v[100:101], s[36:37], v[76:77] op_sel_hi:[1,0,1]
	v_pk_fma_f32 v[102:103], v[102:103], s[36:37], v[66:67] op_sel_hi:[1,0,1]
	v_pk_fma_f32 v[104:105], v[104:105], s[36:37], v[68:69] op_sel_hi:[1,0,1]
	v_pk_fma_f32 v[106:107], v[106:107], s[36:37], v[58:59] op_sel_hi:[1,0,1]
	v_pk_fma_f32 v[108:109], v[108:109], s[36:37], v[60:61] op_sel_hi:[1,0,1]
	v_pk_fma_f32 v[110:111], v[110:111], s[36:37], v[50:51] op_sel_hi:[1,0,1]
	v_pk_fma_f32 v[112:113], v[112:113], s[36:37], v[52:53] op_sel_hi:[1,0,1]
	v_max3_f32 v116, v78, v79, v80
	v_max3_f32 v169, v98, v99, v100
	v_max3_f32 v116, v116, v81, v70
	v_max3_f32 v169, v169, v101, v102
	v_max3_f32 v116, v116, v71, v72
	v_max3_f32 v169, v169, v103, v104
	v_max3_f32 v116, v116, v73, v62
	v_max3_f32 v169, v169, v105, v106
	v_max3_f32 v116, v116, v63, v64
	v_max3_f32 v169, v169, v107, v108
	v_max3_f32 v116, v116, v65, v54
	v_max3_f32 v169, v169, v109, v110
	v_max3_f32 v116, v116, v55, v56
	v_max3_f32 v169, v169, v111, v112
	v_max3_f32 v116, v116, v57, s29
	v_max3_f32 v169, v169, v113, s29
	v_mov_b32_e32 v117, v116
	v_mov_b32_e32 v170, v169
	s_nop 0
	v_permlane16_swap_b32_e32 v116, v117
	v_permlane16_swap_b32_e32 v169, v170
	v_max_f32_e32 v116, v116, v117
	v_max_f32_e32 v169, v169, v170
	v_mov_b32_e32 v117, v116
	v_mov_b32_e32 v170, v169
	s_nop 0
	v_permlane32_swap_b32_e32 v116, v117
	v_permlane32_swap_b32_e32 v169, v170
	v_max_f32_e32 v116, v116, v117
	v_max_f32_e32 v169, v169, v170
	v_max_f32_e32 v121, v166, v116
	v_max_f32_e32 v175, v167, v169
	v_sub_f32_e32 v118, v166, v121
	v_sub_f32_e32 v172, v167, v175
	v_exp_f32_e32 v118, v118
	v_exp_f32_e32 v172, v172
	v_mov_b32_e32 v166, v121
	v_mov_b32_e32 v167, v175
	v_mov_b32_e32 v120, v121
	v_mov_b32_e32 v174, v175
	v_pk_mul_f32 v[46:47], v[46:47], v[118:119] op_sel_hi:[1,0]
	v_pk_mul_f32 v[30:31], v[30:31], v[172:173] op_sel_hi:[1,0]
	v_pk_mul_f32 v[48:49], v[48:49], v[118:119] op_sel_hi:[1,0]
	v_pk_mul_f32 v[32:33], v[32:33], v[172:173] op_sel_hi:[1,0]
	v_pk_mul_f32 v[42:43], v[42:43], v[118:119] op_sel_hi:[1,0]
	v_pk_mul_f32 v[26:27], v[26:27], v[172:173] op_sel_hi:[1,0]
	v_pk_mul_f32 v[44:45], v[44:45], v[118:119] op_sel_hi:[1,0]
	v_pk_mul_f32 v[28:29], v[28:29], v[172:173] op_sel_hi:[1,0]
	v_pk_mul_f32 v[38:39], v[38:39], v[118:119] op_sel_hi:[1,0]
	v_pk_mul_f32 v[22:23], v[22:23], v[172:173] op_sel_hi:[1,0]
	v_pk_mul_f32 v[40:41], v[40:41], v[118:119] op_sel_hi:[1,0]
	v_pk_mul_f32 v[24:25], v[24:25], v[172:173] op_sel_hi:[1,0]
	v_pk_mul_f32 v[34:35], v[34:35], v[118:119] op_sel_hi:[1,0]
	v_pk_mul_f32 v[18:19], v[18:19], v[172:173] op_sel_hi:[1,0]
	v_pk_mul_f32 v[36:37], v[36:37], v[118:119] op_sel_hi:[1,0]
	v_pk_mul_f32 v[20:21], v[20:21], v[172:173] op_sel_hi:[1,0]
	v_pk_add_f32 v[78:79], v[78:79], v[120:121] op_sel_hi:[1,0] neg_lo:[0,1] neg_hi:[0,1]
	v_pk_add_f32 v[98:99], v[98:99], v[174:175] op_sel_hi:[1,0] neg_lo:[0,1] neg_hi:[0,1]
	v_pk_add_f32 v[80:81], v[80:81], v[120:121] op_sel_hi:[1,0] neg_lo:[0,1] neg_hi:[0,1]
	v_pk_add_f32 v[100:101], v[100:101], v[174:175] op_sel_hi:[1,0] neg_lo:[0,1] neg_hi:[0,1]
	v_pk_add_f32 v[70:71], v[70:71], v[120:121] op_sel_hi:[1,0] neg_lo:[0,1] neg_hi:[0,1]
	v_pk_add_f32 v[102:103], v[102:103], v[174:175] op_sel_hi:[1,0] neg_lo:[0,1] neg_hi:[0,1]
	v_pk_add_f32 v[72:73], v[72:73], v[120:121] op_sel_hi:[1,0] neg_lo:[0,1] neg_hi:[0,1]
	v_pk_add_f32 v[104:105], v[104:105], v[174:175] op_sel_hi:[1,0] neg_lo:[0,1] neg_hi:[0,1]
	v_pk_add_f32 v[62:63], v[62:63], v[120:121] op_sel_hi:[1,0] neg_lo:[0,1] neg_hi:[0,1]
	v_pk_add_f32 v[106:107], v[106:107], v[174:175] op_sel_hi:[1,0] neg_lo:[0,1] neg_hi:[0,1]
	v_pk_add_f32 v[64:65], v[64:65], v[120:121] op_sel_hi:[1,0] neg_lo:[0,1] neg_hi:[0,1]
	v_pk_add_f32 v[108:109], v[108:109], v[174:175] op_sel_hi:[1,0] neg_lo:[0,1] neg_hi:[0,1]
	v_pk_add_f32 v[54:55], v[54:55], v[120:121] op_sel_hi:[1,0] neg_lo:[0,1] neg_hi:[0,1]
	v_pk_add_f32 v[110:111], v[110:111], v[174:175] op_sel_hi:[1,0] neg_lo:[0,1] neg_hi:[0,1]
	v_pk_add_f32 v[56:57], v[56:57], v[120:121] op_sel_hi:[1,0] neg_lo:[0,1] neg_hi:[0,1]
	v_pk_add_f32 v[112:113], v[112:113], v[174:175] op_sel_hi:[1,0] neg_lo:[0,1] neg_hi:[0,1]
	v_exp_f32_e32 v78, v78
	v_exp_f32_e32 v98, v98
	v_exp_f32_e32 v79, v79
	v_exp_f32_e32 v99, v99
	v_exp_f32_e32 v80, v80
	v_exp_f32_e32 v100, v100
	v_exp_f32_e32 v81, v81
	v_exp_f32_e32 v101, v101
	v_exp_f32_e32 v70, v70
	v_exp_f32_e32 v102, v102
	v_exp_f32_e32 v71, v71
	v_exp_f32_e32 v103, v103
	v_exp_f32_e32 v72, v72
	v_exp_f32_e32 v104, v104
	v_exp_f32_e32 v73, v73
	v_exp_f32_e32 v105, v105
	v_exp_f32_e32 v62, v62
	v_exp_f32_e32 v106, v106
	v_exp_f32_e32 v63, v63
	v_exp_f32_e32 v107, v107
	v_exp_f32_e32 v64, v64
	v_exp_f32_e32 v108, v108
	v_exp_f32_e32 v65, v65
	v_exp_f32_e32 v109, v109
	v_exp_f32_e32 v54, v54
	v_exp_f32_e32 v110, v110
	v_exp_f32_e32 v55, v55
	v_exp_f32_e32 v111, v111
	v_exp_f32_e32 v56, v56
	v_exp_f32_e32 v112, v112
	v_exp_f32_e32 v57, v57
	v_exp_f32_e32 v113, v113
	v_pk_add_f32 v[82:83], v[78:79], v[80:81]
	v_pk_add_f32 v[74:75], v[98:99], v[100:101]
	v_pk_add_f32 v[84:85], v[70:71], v[72:73]
	v_pk_add_f32 v[76:77], v[102:103], v[104:105]
	v_pk_add_f32 v[86:87], v[62:63], v[64:65]
	v_pk_add_f32 v[66:67], v[106:107], v[108:109]
	v_pk_add_f32 v[88:89], v[54:55], v[56:57]
	v_pk_add_f32 v[68:69], v[110:111], v[112:113]
	v_pk_add_f32 v[82:83], v[82:83], v[84:85]
	v_pk_add_f32 v[74:75], v[74:75], v[76:77]
	v_pk_add_f32 v[86:87], v[86:87], v[88:89]
	v_pk_add_f32 v[66:67], v[66:67], v[68:69]
	v_pk_add_f32 v[82:83], v[82:83], v[86:87]
	v_pk_add_f32 v[74:75], v[74:75], v[66:67]
	v_add_f32_e32 v82, v82, v83
	v_add_f32_e32 v74, v74, v75
	v_fma_f32 v160, v160, v118, v82
	v_fma_f32 v161, v161, v172, v74
	v_cvt_pk_bf16_f32 v73, v72, v73
	v_cvt_pk_bf16_f32 v105, v104, v105
	v_cvt_pk_bf16_f32 v72, v70, v71
	v_cvt_pk_bf16_f32 v104, v102, v103
	v_cvt_pk_bf16_f32 v71, v80, v81
	v_cvt_pk_bf16_f32 v103, v100, v101
	v_cvt_pk_bf16_f32 v70, v78, v79
	v_cvt_pk_bf16_f32 v102, v98, v99
	v_cvt_pk_bf16_f32 v62, v62, v63
	v_cvt_pk_bf16_f32 v106, v106, v107
	v_cvt_pk_bf16_f32 v63, v64, v65
	v_cvt_pk_bf16_f32 v107, v108, v109
	v_cvt_pk_bf16_f32 v64, v54, v55
	v_cvt_pk_bf16_f32 v108, v110, v111
	v_cvt_pk_bf16_f32 v65, v56, v57
	v_cvt_pk_bf16_f32 v109, v112, v113

.LBB0_430:
	s_andn2_b64 vcc, exec, s[6:7]
	s_cbranch_vccnz .LBB0_438
	v_cmp_ne_u32_e32 vcc, 0, v139
	s_cbranch_vccz .Lsel_fast
	v_add_u32_e32 v54, s13, v196
	v_sub_u32_e32 v0, s14, v140
	v_add_u32_e32 v62, v54, v194
	v_add_u32_e32 v89, v54, v195
	v_lshl_add_u32 v0, v0, 2, v216
	s_cmp_lg_u64 s[44:45], 0
	s_movk_i32 s98, 0xfec
	s_cselect_b32 s98, 0xffc, s98
	v_add_u32_e32 v230, s98, v0
	v_add_u32_e32 v231, 0xfec, v0
	ds_read_b128 v[64:67], v62 offset:16384
	ds_read_b128 v[54:57], v89 offset:16384
	ds_read_b128 v[68:71], v62 offset:18432
	ds_read_b128 v[58:61], v89 offset:18432
	ds_read_b128 v[72:75], v62 offset:20480
	ds_read_b128 v[76:79], v89 offset:20480
	ds_read_b128 v[80:83], v62 offset:22528
	ds_read_b128 v[84:87], v89 offset:22528
	ds_read2_b32 v[90:91], v230 offset1:1
	ds_read2_b32 v[92:93], v230 offset0:2 offset1:3
	ds_read2_b32 v[94:95], v230 offset0:16 offset1:17
	ds_read2_b32 v[96:97], v230 offset0:18 offset1:19
	s_waitcnt lgkmcnt(4)
	ds_read2_b32 v[98:99], v230 offset0:32 offset1:33
	ds_read2_b32 v[100:101], v230 offset0:34 offset1:35
	ds_read2_b32 v[154:155], v230 offset0:48 offset1:49
	ds_read2_b32 v[156:157], v230 offset0:50 offset1:51
	s_cbranch_scc0 .Lp1v_m1
	s_cmp_lg_u64 s[42:43], 0
	s_cbranch_scc0 .Lp1v_only0
	v_mfma_f32_16x16x32_bf16 v[170:173], v[64:67], v[2:5], 0
	v_mfma_f32_16x16x32_bf16 v[174:177], v[68:71], v[2:5], 0
	v_mfma_f32_16x16x32_bf16 v[170:173], v[54:57], v[6:9], v[170:173]
	v_mfma_f32_16x16x32_bf16 v[178:181], v[72:75], v[2:5], 0
	v_mfma_f32_16x16x32_bf16 v[174:177], v[58:61], v[6:9], v[174:177]
	v_mfma_f32_16x16x32_bf16 v[182:185], v[80:83], v[2:5], 0
	v_mfma_f32_16x16x32_bf16 v[178:181], v[76:79], v[6:9], v[178:181]
	v_mfma_f32_16x16x32_bf16 v[182:185], v[84:87], v[6:9], v[182:185]
	v_mfma_f32_16x16x32_bf16 v[64:67], v[64:67], v[10:13], 0
	v_mfma_f32_16x16x32_bf16 v[68:71], v[68:71], v[10:13], 0
	v_mfma_f32_16x16x32_bf16 v[64:67], v[54:57], v[14:17], v[64:67]
	v_mfma_f32_16x16x32_bf16 v[72:75], v[72:75], v[10:13], 0
	v_mfma_f32_16x16x32_bf16 v[68:71], v[58:61], v[14:17], v[68:71]
	v_mfma_f32_16x16x32_bf16 v[80:83], v[80:83], v[10:13], 0
	v_mfma_f32_16x16x32_bf16 v[72:75], v[76:79], v[14:17], v[72:75]
	v_mfma_f32_16x16x32_bf16 v[80:83], v[84:87], v[14:17], v[80:83]
	s_waitcnt lgkmcnt(0)
	v_pk_fma_f32 v[170:171], v[170:171], s[36:37], v[90:91] op_sel_hi:[1,0,1]
	v_pk_fma_f32 v[172:173], v[172:173], s[36:37], v[92:93] op_sel_hi:[1,0,1]
	v_pk_fma_f32 v[174:175], v[174:175], s[36:37], v[94:95] op_sel_hi:[1,0,1]
	v_pk_fma_f32 v[176:177], v[176:177], s[36:37], v[96:97] op_sel_hi:[1,0,1]
	v_pk_fma_f32 v[178:179], v[178:179], s[36:37], v[98:99] op_sel_hi:[1,0,1]
	v_pk_fma_f32 v[180:181], v[180:181], s[36:37], v[100:101] op_sel_hi:[1,0,1]
	v_pk_fma_f32 v[182:183], v[182:183], s[36:37], v[154:155] op_sel_hi:[1,0,1]
	v_pk_fma_f32 v[184:185], v[184:185], s[36:37], v[156:157] op_sel_hi:[1,0,1]
	ds_read2_b32 v[90:91], v231 offset1:1
	ds_read2_b32 v[92:93], v231 offset0:2 offset1:3
	ds_read2_b32 v[94:95], v231 offset0:16 offset1:17
	ds_read2_b32 v[96:97], v231 offset0:18 offset1:19
	ds_read2_b32 v[98:99], v231 offset0:32 offset1:33
	ds_read2_b32 v[100:101], v231 offset0:34 offset1:35
	ds_read2_b32 v[154:155], v231 offset0:48 offset1:49
	ds_read2_b32 v[156:157], v231 offset0:50 offset1:51
	v_max3_f32 v186, v170, v171, v172
	v_max3_f32 v186, v186, v173, v174
	v_max3_f32 v186, v186, v175, v176
	v_max3_f32 v186, v186, v177, v178
	v_max3_f32 v186, v186, v179, v180
	v_max3_f32 v186, v186, v181, v182
	v_max3_f32 v186, v186, v183, v184
	v_max3_f32 v186, v186, v185, s29
	v_mov_b32_e32 v187, v186
	s_nop 1
	v_permlane16_swap_b32_e32 v186, v187
	v_max_f32_e32 v186, v186, v187
	v_mov_b32_e32 v187, v186
	s_nop 1
	v_permlane32_swap_b32_e32 v186, v187
	v_max_f32_e32 v186, v186, v187
	v_cndmask_b32_e64 v186, v148, v186, s[44:45]
	v_max_f32_e32 v187, v160, v186
	s_waitcnt lgkmcnt(0)
	v_pk_fma_f32 v[64:65], v[64:65], s[36:37], v[90:91] op_sel_hi:[1,0,1]
	v_pk_fma_f32 v[66:67], v[66:67], s[36:37], v[92:93] op_sel_hi:[1,0,1]
	v_pk_fma_f32 v[68:69], v[68:69], s[36:37], v[94:95] op_sel_hi:[1,0,1]
	v_pk_fma_f32 v[70:71], v[70:71], s[36:37], v[96:97] op_sel_hi:[1,0,1]
	v_pk_fma_f32 v[72:73], v[72:73], s[36:37], v[98:99] op_sel_hi:[1,0,1]
	v_pk_fma_f32 v[74:75], v[74:75], s[36:37], v[100:101] op_sel_hi:[1,0,1]
	v_pk_fma_f32 v[80:81], v[80:81], s[36:37], v[154:155] op_sel_hi:[1,0,1]
	v_pk_fma_f32 v[82:83], v[82:83], s[36:37], v[156:157] op_sel_hi:[1,0,1]
	v_max3_f32 v76, v64, v65, v66
	v_max3_f32 v76, v76, v67, v68
	v_max3_f32 v76, v76, v69, v70
	v_max3_f32 v76, v76, v71, v72
	v_max3_f32 v76, v76, v73, v74
	v_max3_f32 v76, v76, v75, v80
	v_max3_f32 v76, v76, v81, v82
	v_max3_f32 v76, v76, v83, s29
	v_mov_b32_e32 v77, v76
	s_nop 1
	v_permlane16_swap_b32_e32 v76, v77
	v_max_f32_e32 v76, v76, v77
	v_mov_b32_e32 v77, v76
	s_nop 1
	v_permlane32_swap_b32_e32 v76, v77
	v_max_f32_e32 v76, v76, v77
	v_cndmask_b32_e64 v76, v148, v76, s[42:43]
	v_max_f32_e32 v77, v161, v76
	v_sub_f32_e32 v248, v160, v187
	v_sub_f32_e32 v0, v161, v77
	v_exp_f32_e32 v236, v248
	v_exp_f32_e32 v0, v0
	v_cndmask_b32_e64 v246, v209, v187, s[44:45]
	v_cndmask_b32_e64 v78, v209, v77, s[42:43]
	v_mov_b32_e32 v160, v187
	v_mov_b32_e32 v161, v77
	v_pk_mul_f32 v[36:37], v[36:37], v[236:237] op_sel_hi:[1,0]
	v_pk_mul_f32 v[32:33], v[32:33], v[0:1] op_sel_hi:[1,0]
	v_pk_mul_f32 v[34:35], v[34:35], v[236:237] op_sel_hi:[1,0]
	v_pk_mul_f32 v[30:31], v[30:31], v[0:1] op_sel_hi:[1,0]
	v_pk_mul_f32 v[48:49], v[48:49], v[236:237] op_sel_hi:[1,0]
	v_pk_mul_f32 v[28:29], v[28:29], v[0:1] op_sel_hi:[1,0]
	v_pk_mul_f32 v[46:47], v[46:47], v[236:237] op_sel_hi:[1,0]
	v_pk_mul_f32 v[26:27], v[26:27], v[0:1] op_sel_hi:[1,0]
	v_pk_mul_f32 v[44:45], v[44:45], v[236:237] op_sel_hi:[1,0]
	v_pk_mul_f32 v[24:25], v[24:25], v[0:1] op_sel_hi:[1,0]
	v_pk_mul_f32 v[42:43], v[42:43], v[236:237] op_sel_hi:[1,0]
	v_pk_mul_f32 v[22:23], v[22:23], v[0:1] op_sel_hi:[1,0]
	v_pk_mul_f32 v[52:53], v[52:53], v[236:237] op_sel_hi:[1,0]
	v_pk_mul_f32 v[20:21], v[20:21], v[0:1] op_sel_hi:[1,0]
	v_pk_mul_f32 v[50:51], v[50:51], v[236:237] op_sel_hi:[1,0]
	v_pk_mul_f32 v[18:19], v[18:19], v[0:1] op_sel_hi:[1,0]
	v_pk_add_f32 v[170:171], v[170:171], v[246:247] op_sel_hi:[1,0] neg_lo:[0,1] neg_hi:[0,1]
	v_pk_add_f32 v[64:65], v[64:65], v[78:79] op_sel_hi:[1,0] neg_lo:[0,1] neg_hi:[0,1]
	v_pk_add_f32 v[172:173], v[172:173], v[246:247] op_sel_hi:[1,0] neg_lo:[0,1] neg_hi:[0,1]
	v_pk_add_f32 v[66:67], v[66:67], v[78:79] op_sel_hi:[1,0] neg_lo:[0,1] neg_hi:[0,1]
	v_pk_add_f32 v[174:175], v[174:175], v[246:247] op_sel_hi:[1,0] neg_lo:[0,1] neg_hi:[0,1]
	v_pk_add_f32 v[68:69], v[68:69], v[78:79] op_sel_hi:[1,0] neg_lo:[0,1] neg_hi:[0,1]
	v_pk_add_f32 v[176:177], v[176:177], v[246:247] op_sel_hi:[1,0] neg_lo:[0,1] neg_hi:[0,1]
	v_pk_add_f32 v[70:71], v[70:71], v[78:79] op_sel_hi:[1,0] neg_lo:[0,1] neg_hi:[0,1]
	v_pk_add_f32 v[178:179], v[178:179], v[246:247] op_sel_hi:[1,0] neg_lo:[0,1] neg_hi:[0,1]
	v_pk_add_f32 v[72:73], v[72:73], v[78:79] op_sel_hi:[1,0] neg_lo:[0,1] neg_hi:[0,1]
	v_pk_add_f32 v[180:181], v[180:181], v[246:247] op_sel_hi:[1,0] neg_lo:[0,1] neg_hi:[0,1]
	v_pk_add_f32 v[74:75], v[74:75], v[78:79] op_sel_hi:[1,0] neg_lo:[0,1] neg_hi:[0,1]
	v_pk_add_f32 v[182:183], v[182:183], v[246:247] op_sel_hi:[1,0] neg_lo:[0,1] neg_hi:[0,1]
	v_pk_add_f32 v[80:81], v[80:81], v[78:79] op_sel_hi:[1,0] neg_lo:[0,1] neg_hi:[0,1]
	v_pk_add_f32 v[184:185], v[184:185], v[246:247] op_sel_hi:[1,0] neg_lo:[0,1] neg_hi:[0,1]
	v_pk_add_f32 v[82:83], v[82:83], v[78:79] op_sel_hi:[1,0] neg_lo:[0,1] neg_hi:[0,1]
	v_exp_f32_e32 v170, v170
	v_exp_f32_e32 v64, v64
	v_exp_f32_e32 v171, v171
	v_exp_f32_e32 v65, v65
	v_exp_f32_e32 v172, v172
	v_exp_f32_e32 v66, v66
	v_exp_f32_e32 v173, v173
	v_exp_f32_e32 v67, v67
	v_exp_f32_e32 v174, v174
	v_exp_f32_e32 v68, v68
	v_exp_f32_e32 v175, v175
	v_exp_f32_e32 v69, v69
	v_exp_f32_e32 v176, v176
	v_exp_f32_e32 v70, v70
	v_exp_f32_e32 v177, v177
	v_exp_f32_e32 v71, v71
	v_exp_f32_e32 v178, v178
	v_exp_f32_e32 v72, v72
	v_exp_f32_e32 v179, v179
	v_exp_f32_e32 v73, v73
	v_exp_f32_e32 v180, v180
	v_exp_f32_e32 v74, v74
	v_exp_f32_e32 v181, v181
	v_exp_f32_e32 v75, v75
	v_exp_f32_e32 v182, v182
	v_exp_f32_e32 v80, v80
	v_exp_f32_e32 v183, v183
	v_exp_f32_e32 v81, v81
	v_exp_f32_e32 v184, v184
	v_exp_f32_e32 v82, v82
	v_exp_f32_e32 v185, v185
	v_exp_f32_e32 v83, v83
	v_pk_add_f32 v[238:239], v[170:171], v[172:173]
	v_pk_add_f32 v[84:85], v[64:65], v[66:67]
	v_pk_add_f32 v[240:241], v[174:175], v[176:177]
	v_pk_add_f32 v[86:87], v[68:69], v[70:71]
	v_pk_add_f32 v[242:243], v[178:179], v[180:181]
	v_pk_add_f32 v[76:77], v[72:73], v[74:75]
	v_pk_add_f32 v[244:245], v[182:183], v[184:185]
	v_pk_add_f32 v[78:79], v[80:81], v[82:83]
	v_pk_add_f32 v[238:239], v[238:239], v[240:241]
	v_pk_add_f32 v[84:85], v[84:85], v[86:87]
	v_pk_add_f32 v[242:243], v[242:243], v[244:245]
	v_pk_add_f32 v[76:77], v[76:77], v[78:79]
	v_pk_add_f32 v[238:239], v[238:239], v[242:243]
	v_pk_add_f32 v[84:85], v[84:85], v[76:77]
	v_add_f32_e32 v238, v238, v239
	v_add_f32_e32 v84, v84, v85
	v_fma_f32 v144, v144, v236, v238
	v_fma_f32 v145, v145, v0, v84
	v_cvt_pk_bf16_f32 v58, v170, v171
	v_cvt_pk_bf16_f32 v67, v66, v67
	v_cvt_pk_bf16_f32 v59, v172, v173
	v_cvt_pk_bf16_f32 v66, v64, v65
	v_cvt_pk_bf16_f32 v60, v174, v175
	v_cvt_pk_bf16_f32 v68, v68, v69
	v_cvt_pk_bf16_f32 v61, v176, v177
	v_cvt_pk_bf16_f32 v69, v70, v71
	v_cvt_pk_bf16_f32 v54, v178, v179
	v_cvt_pk_bf16_f32 v62, v72, v73
	v_cvt_pk_bf16_f32 v55, v180, v181
	v_cvt_pk_bf16_f32 v63, v74, v75
	v_cvt_pk_bf16_f32 v56, v182, v183
	v_cvt_pk_bf16_f32 v64, v80, v81
	v_cvt_pk_bf16_f32 v57, v184, v185
	v_cvt_pk_bf16_f32 v65, v82, v83
	s_branch .LBB0_446
.Lp1v_only0:
	v_mfma_f32_16x16x32_bf16 v[170:173], v[64:67], v[2:5], 0
	v_mfma_f32_16x16x32_bf16 v[174:177], v[68:71], v[2:5], 0
	v_mfma_f32_16x16x32_bf16 v[170:173], v[54:57], v[6:9], v[170:173]
	v_mfma_f32_16x16x32_bf16 v[178:181], v[72:75], v[2:5], 0
	v_mfma_f32_16x16x32_bf16 v[174:177], v[58:61], v[6:9], v[174:177]
	v_mfma_f32_16x16x32_bf16 v[182:185], v[80:83], v[2:5], 0
	v_mfma_f32_16x16x32_bf16 v[178:181], v[76:79], v[6:9], v[178:181]
	v_mfma_f32_16x16x32_bf16 v[182:185], v[84:87], v[6:9], v[182:185]
	s_nop 7
	s_nop 7
	s_waitcnt lgkmcnt(0)
	v_pk_fma_f32 v[170:171], v[170:171], s[36:37], v[90:91] op_sel_hi:[1,0,1]
	v_pk_fma_f32 v[172:173], v[172:173], s[36:37], v[92:93] op_sel_hi:[1,0,1]
	v_pk_fma_f32 v[174:175], v[174:175], s[36:37], v[94:95] op_sel_hi:[1,0,1]
	v_pk_fma_f32 v[176:177], v[176:177], s[36:37], v[96:97] op_sel_hi:[1,0,1]
	v_pk_fma_f32 v[178:179], v[178:179], s[36:37], v[98:99] op_sel_hi:[1,0,1]
	v_pk_fma_f32 v[180:181], v[180:181], s[36:37], v[100:101] op_sel_hi:[1,0,1]
	v_pk_fma_f32 v[182:183], v[182:183], s[36:37], v[154:155] op_sel_hi:[1,0,1]
	v_pk_fma_f32 v[184:185], v[184:185], s[36:37], v[156:157] op_sel_hi:[1,0,1]
	v_max3_f32 v186, v170, v171, v172
	v_max3_f32 v186, v186, v173, v174
	v_max3_f32 v186, v186, v175, v176
	v_max3_f32 v186, v186, v177, v178
	v_max3_f32 v186, v186, v179, v180
	v_max3_f32 v186, v186, v181, v182
	v_max3_f32 v186, v186, v183, v184
	v_max3_f32 v186, v186, v185, s29
	v_mov_b32_e32 v187, v186
	s_nop 1
	v_permlane16_swap_b32_e32 v186, v187
	v_max_f32_e32 v186, v186, v187
	v_mov_b32_e32 v187, v186
	s_nop 1
	v_permlane32_swap_b32_e32 v186, v187
	v_max_f32_e32 v186, v186, v187
	v_cndmask_b32_e64 v186, v148, v186, s[44:45]
	v_max_f32_e32 v187, v160, v186
	v_sub_f32_e32 v248, v160, v187
	v_exp_f32_e32 v236, v248
	v_cndmask_b32_e64 v246, v209, v187, s[44:45]
	v_mov_b32_e32 v160, v187
	v_pk_mul_f32 v[36:37], v[36:37], v[236:237] op_sel_hi:[1,0]
	v_pk_mul_f32 v[34:35], v[34:35], v[236:237] op_sel_hi:[1,0]
	v_pk_mul_f32 v[48:49], v[48:49], v[236:237] op_sel_hi:[1,0]
	v_pk_mul_f32 v[46:47], v[46:47], v[236:237] op_sel_hi:[1,0]
	v_pk_mul_f32 v[44:45], v[44:45], v[236:237] op_sel_hi:[1,0]
	v_pk_mul_f32 v[42:43], v[42:43], v[236:237] op_sel_hi:[1,0]
	v_pk_mul_f32 v[52:53], v[52:53], v[236:237] op_sel_hi:[1,0]
	v_pk_mul_f32 v[50:51], v[50:51], v[236:237] op_sel_hi:[1,0]
	v_pk_add_f32 v[170:171], v[170:171], v[246:247] op_sel_hi:[1,0] neg_lo:[0,1] neg_hi:[0,1]
	v_pk_add_f32 v[172:173], v[172:173], v[246:247] op_sel_hi:[1,0] neg_lo:[0,1] neg_hi:[0,1]
	v_pk_add_f32 v[174:175], v[174:175], v[246:247] op_sel_hi:[1,0] neg_lo:[0,1] neg_hi:[0,1]
	v_pk_add_f32 v[176:177], v[176:177], v[246:247] op_sel_hi:[1,0] neg_lo:[0,1] neg_hi:[0,1]
	v_pk_add_f32 v[178:179], v[178:179], v[246:247] op_sel_hi:[1,0] neg_lo:[0,1] neg_hi:[0,1]
	v_pk_add_f32 v[180:181], v[180:181], v[246:247] op_sel_hi:[1,0] neg_lo:[0,1] neg_hi:[0,1]
	v_pk_add_f32 v[182:183], v[182:183], v[246:247] op_sel_hi:[1,0] neg_lo:[0,1] neg_hi:[0,1]
	v_pk_add_f32 v[184:185], v[184:185], v[246:247] op_sel_hi:[1,0] neg_lo:[0,1] neg_hi:[0,1]
	v_exp_f32_e32 v170, v170
	v_exp_f32_e32 v171, v171
	v_exp_f32_e32 v172, v172
	v_exp_f32_e32 v173, v173
	v_exp_f32_e32 v174, v174
	v_exp_f32_e32 v175, v175
	v_exp_f32_e32 v176, v176
	v_exp_f32_e32 v177, v177
	v_exp_f32_e32 v178, v178
	v_exp_f32_e32 v179, v179
	v_exp_f32_e32 v180, v180
	v_exp_f32_e32 v181, v181
	v_exp_f32_e32 v182, v182
	v_exp_f32_e32 v183, v183
	v_exp_f32_e32 v184, v184
	v_exp_f32_e32 v185, v185
	s_nop 0
	v_pk_add_f32 v[238:239], v[170:171], v[172:173]
	v_pk_add_f32 v[240:241], v[174:175], v[176:177]
	v_pk_add_f32 v[242:243], v[178:179], v[180:181]
	v_pk_add_f32 v[244:245], v[182:183], v[184:185]
	v_pk_add_f32 v[238:239], v[238:239], v[240:241]
	v_pk_add_f32 v[242:243], v[242:243], v[244:245]
	s_nop 0
	v_pk_add_f32 v[238:239], v[238:239], v[242:243]
	s_nop 0
	v_add_f32_e32 v238, v238, v239
	v_fma_f32 v144, v144, v236, v238
	v_cvt_pk_bf16_f32 v58, v170, v171
	v_cvt_pk_bf16_f32 v59, v172, v173
	v_cvt_pk_bf16_f32 v60, v174, v175
	v_cvt_pk_bf16_f32 v61, v176, v177
	v_cvt_pk_bf16_f32 v54, v178, v179
	v_cvt_pk_bf16_f32 v55, v180, v181
	v_cvt_pk_bf16_f32 v56, v182, v183
	v_cvt_pk_bf16_f32 v57, v184, v185
	s_branch .LBB0_445
.Lp1v_m1:
	v_mfma_f32_16x16x32_bf16 v[64:67], v[64:67], v[10:13], 0
	v_mfma_f32_16x16x32_bf16 v[68:71], v[68:71], v[10:13], 0
	v_mfma_f32_16x16x32_bf16 v[64:67], v[54:57], v[14:17], v[64:67]
	v_mfma_f32_16x16x32_bf16 v[72:75], v[72:75], v[10:13], 0
	v_mfma_f32_16x16x32_bf16 v[68:71], v[58:61], v[14:17], v[68:71]
	v_mfma_f32_16x16x32_bf16 v[80:83], v[80:83], v[10:13], 0
	v_mfma_f32_16x16x32_bf16 v[72:75], v[76:79], v[14:17], v[72:75]
	v_mfma_f32_16x16x32_bf16 v[80:83], v[84:87], v[14:17], v[80:83]
	s_nop 7
	s_nop 7
	v_mov_b32_e32 v54, 0
	v_mov_b32_e32 v55, v54
	v_mov_b32_e32 v56, v54
	v_mov_b32_e32 v57, v54
	v_mov_b32_e32 v58, v54
	v_mov_b32_e32 v59, v54
	v_mov_b32_e32 v60, v54
	v_mov_b32_e32 v61, v54
	s_waitcnt lgkmcnt(0)
	v_pk_fma_f32 v[64:65], v[64:65], s[36:37], v[90:91] op_sel_hi:[1,0,1]
	v_pk_fma_f32 v[66:67], v[66:67], s[36:37], v[92:93] op_sel_hi:[1,0,1]
	v_pk_fma_f32 v[68:69], v[68:69], s[36:37], v[94:95] op_sel_hi:[1,0,1]
	v_pk_fma_f32 v[70:71], v[70:71], s[36:37], v[96:97] op_sel_hi:[1,0,1]
	v_pk_fma_f32 v[72:73], v[72:73], s[36:37], v[98:99] op_sel_hi:[1,0,1]
	v_pk_fma_f32 v[74:75], v[74:75], s[36:37], v[100:101] op_sel_hi:[1,0,1]
	v_pk_fma_f32 v[80:81], v[80:81], s[36:37], v[154:155] op_sel_hi:[1,0,1]
	v_pk_fma_f32 v[82:83], v[82:83], s[36:37], v[156:157] op_sel_hi:[1,0,1]
	v_max3_f32 v76, v64, v65, v66
	v_max3_f32 v76, v76, v67, v68
	v_max3_f32 v76, v76, v69, v70
	v_max3_f32 v76, v76, v71, v72
	v_max3_f32 v76, v76, v73, v74
	v_max3_f32 v76, v76, v75, v80
	v_max3_f32 v76, v76, v81, v82
	v_max3_f32 v76, v76, v83, s29
	v_mov_b32_e32 v77, v76
	s_nop 1
	v_permlane16_swap_b32_e32 v76, v77
	v_max_f32_e32 v76, v76, v77
	v_mov_b32_e32 v77, v76
	s_nop 1
	v_permlane32_swap_b32_e32 v76, v77
	v_max_f32_e32 v76, v76, v77
	v_cndmask_b32_e64 v76, v148, v76, s[42:43]
	v_max_f32_e32 v77, v161, v76
	v_sub_f32_e32 v0, v161, v77
	v_exp_f32_e32 v0, v0
	v_cndmask_b32_e64 v78, v209, v77, s[42:43]
	v_mov_b32_e32 v161, v77
	v_pk_mul_f32 v[32:33], v[32:33], v[0:1] op_sel_hi:[1,0]
	v_pk_mul_f32 v[30:31], v[30:31], v[0:1] op_sel_hi:[1,0]
	v_pk_mul_f32 v[28:29], v[28:29], v[0:1] op_sel_hi:[1,0]
	v_pk_mul_f32 v[26:27], v[26:27], v[0:1] op_sel_hi:[1,0]
	v_pk_mul_f32 v[24:25], v[24:25], v[0:1] op_sel_hi:[1,0]
	v_pk_mul_f32 v[22:23], v[22:23], v[0:1] op_sel_hi:[1,0]
	v_pk_mul_f32 v[20:21], v[20:21], v[0:1] op_sel_hi:[1,0]
	v_pk_mul_f32 v[18:19], v[18:19], v[0:1] op_sel_hi:[1,0]
	v_pk_add_f32 v[64:65], v[64:65], v[78:79] op_sel_hi:[1,0] neg_lo:[0,1] neg_hi:[0,1]
	v_pk_add_f32 v[66:67], v[66:67], v[78:79] op_sel_hi:[1,0] neg_lo:[0,1] neg_hi:[0,1]
	v_pk_add_f32 v[68:69], v[68:69], v[78:79] op_sel_hi:[1,0] neg_lo:[0,1] neg_hi:[0,1]
	v_pk_add_f32 v[70:71], v[70:71], v[78:79] op_sel_hi:[1,0] neg_lo:[0,1] neg_hi:[0,1]
	v_pk_add_f32 v[72:73], v[72:73], v[78:79] op_sel_hi:[1,0] neg_lo:[0,1] neg_hi:[0,1]
	v_pk_add_f32 v[74:75], v[74:75], v[78:79] op_sel_hi:[1,0] neg_lo:[0,1] neg_hi:[0,1]
	v_pk_add_f32 v[80:81], v[80:81], v[78:79] op_sel_hi:[1,0] neg_lo:[0,1] neg_hi:[0,1]
	v_pk_add_f32 v[82:83], v[82:83], v[78:79] op_sel_hi:[1,0] neg_lo:[0,1] neg_hi:[0,1]
	v_exp_f32_e32 v64, v64
	v_exp_f32_e32 v65, v65
	v_exp_f32_e32 v66, v66
	v_exp_f32_e32 v67, v67
	v_exp_f32_e32 v68, v68
	v_exp_f32_e32 v69, v69
	v_exp_f32_e32 v70, v70
	v_exp_f32_e32 v71, v71
	v_exp_f32_e32 v72, v72
	v_exp_f32_e32 v73, v73
	v_exp_f32_e32 v74, v74
	v_exp_f32_e32 v75, v75
	v_exp_f32_e32 v80, v80
	v_exp_f32_e32 v81, v81
	v_exp_f32_e32 v82, v82
	v_exp_f32_e32 v83, v83
	s_nop 0
	v_pk_add_f32 v[84:85], v[64:65], v[66:67]
	v_pk_add_f32 v[86:87], v[68:69], v[70:71]
	v_pk_add_f32 v[76:77], v[72:73], v[74:75]
	v_pk_add_f32 v[78:79], v[80:81], v[82:83]
	v_pk_add_f32 v[84:85], v[84:85], v[86:87]
	v_pk_add_f32 v[76:77], v[76:77], v[78:79]
	s_nop 0
	v_pk_add_f32 v[84:85], v[84:85], v[76:77]
	s_nop 0
	v_add_f32_e32 v84, v84, v85
	v_fma_f32 v145, v145, v0, v84
	v_cvt_pk_bf16_f32 v67, v66, v67
	v_cvt_pk_bf16_f32 v66, v64, v65
	v_cvt_pk_bf16_f32 v68, v68, v69
	v_cvt_pk_bf16_f32 v69, v70, v71
	v_cvt_pk_bf16_f32 v62, v72, v73
	v_cvt_pk_bf16_f32 v63, v74, v75
	v_cvt_pk_bf16_f32 v64, v80, v81
	v_cvt_pk_bf16_f32 v65, v82, v83
	s_branch .LBB0_446

.LBB0_439:
	s_andn2_b64 vcc, exec, s[6:7]
	s_cbranch_vccnz .LBB0_448
	v_and_b32_e32 v0, 1, v164
	v_cmp_eq_u32_e64 s[42:43], 1, v0
	v_and_b32_e32 v0, 1, v162
	v_cmp_eq_u32_e64 s[44:45], 1, v0
	s_or_b64 s[6:7], s[44:45], s[42:43]
	v_cndmask_b32_e64 v54, 0, 1, s[6:7]
	v_cmp_ne_u32_e32 vcc, 0, v54
	s_cbranch_vccz .Lsel_fast
	v_add_u32_e32 v54, s13, v196
	v_add_u32_e32 v62, v54, v194
	v_add_u32_e32 v0, v54, v195
	s_cmp_lg_u64 s[44:45], 0
	ds_read_b128 v[64:67], v62 offset:16384
	ds_read_b128 v[54:57], v0 offset:16384
	ds_read_b128 v[68:71], v62 offset:18432
	ds_read_b128 v[58:61], v0 offset:18432
	ds_read_b128 v[72:75], v62 offset:20480
	ds_read_b128 v[76:79], v0 offset:20480
	ds_read_b128 v[80:83], v62 offset:22528
	ds_read_b128 v[84:87], v0 offset:22528
	ds_read_b32 v188, v193
	s_waitcnt lgkmcnt(0)
	s_cbranch_scc0 .Lp2v_m1
	s_cmp_lg_u64 s[42:43], 0
	s_cbranch_scc0 .Lp2v_only0
	v_mfma_f32_16x16x32_bf16 v[170:173], v[64:67], v[2:5], 0
	v_mfma_f32_16x16x32_bf16 v[174:177], v[68:71], v[2:5], 0
	v_mfma_f32_16x16x32_bf16 v[170:173], v[54:57], v[6:9], v[170:173]
	v_mfma_f32_16x16x32_bf16 v[178:181], v[72:75], v[2:5], 0
	v_mfma_f32_16x16x32_bf16 v[174:177], v[58:61], v[6:9], v[174:177]
	v_mfma_f32_16x16x32_bf16 v[182:185], v[80:83], v[2:5], 0
	v_mfma_f32_16x16x32_bf16 v[178:181], v[76:79], v[6:9], v[178:181]
	v_mfma_f32_16x16x32_bf16 v[182:185], v[84:87], v[6:9], v[182:185]
	v_mfma_f32_16x16x32_bf16 v[64:67], v[64:67], v[10:13], 0
	v_mfma_f32_16x16x32_bf16 v[68:71], v[68:71], v[10:13], 0
	v_mfma_f32_16x16x32_bf16 v[64:67], v[54:57], v[14:17], v[64:67]
	v_mfma_f32_16x16x32_bf16 v[72:75], v[72:75], v[10:13], 0
	v_mfma_f32_16x16x32_bf16 v[68:71], v[58:61], v[14:17], v[68:71]
	v_mfma_f32_16x16x32_bf16 v[80:83], v[80:83], v[10:13], 0
	v_mfma_f32_16x16x32_bf16 v[72:75], v[76:79], v[14:17], v[72:75]
	v_mfma_f32_16x16x32_bf16 v[80:83], v[84:87], v[14:17], v[80:83]
	s_nop 7
	v_max3_f32 v186, v170, v171, v172
	v_max3_f32 v76, v64, v65, v66
	v_max3_f32 v186, v186, v173, v174
	v_max3_f32 v76, v76, v67, v68
	v_max3_f32 v186, v186, v175, v176
	v_max3_f32 v76, v76, v69, v70
	v_max3_f32 v186, v186, v177, v178
	v_max3_f32 v76, v76, v71, v72
	v_max3_f32 v186, v186, v179, v180
	v_max3_f32 v76, v76, v73, v74
	v_max3_f32 v186, v186, v181, v182
	v_max3_f32 v76, v76, v75, v80
	v_max3_f32 v186, v186, v183, v184
	v_max3_f32 v76, v76, v81, v82
	v_max_f32_e32 v186, v186, v185
	v_max_f32_e32 v76, v76, v83
	v_mov_b32_e32 v187, v186
	v_mov_b32_e32 v77, v76
	s_nop 0
	v_permlane16_swap_b32_e32 v186, v187
	v_permlane16_swap_b32_e32 v76, v77
	v_max_f32_e32 v186, v186, v187
	v_max_f32_e32 v76, v76, v77
	v_mov_b32_e32 v187, v186
	v_mov_b32_e32 v77, v76
	s_nop 0
	v_permlane32_swap_b32_e32 v186, v187
	v_permlane32_swap_b32_e32 v76, v77
	v_max_f32_e32 v186, v186, v187
	v_max_f32_e32 v76, v76, v77
	v_fma_f32 v186, v186, s36, v188
	v_fma_f32 v76, v76, s36, v188
	v_max_f32_e32 v186, s29, v186
	v_max_f32_e32 v76, s29, v76
	v_cndmask_b32_e64 v186, v148, v186, s[44:45]
	v_cndmask_b32_e64 v76, v148, v76, s[42:43]
	v_max_f32_e32 v187, v160, v186
	v_max_f32_e32 v77, v161, v76
	v_sub_f32_e32 v248, v160, v187
	v_sub_f32_e32 v0, v161, v77
	v_exp_f32_e32 v236, v248
	v_exp_f32_e32 v0, v0
	v_cndmask_b32_e64 v186, v209, v187, s[44:45]
	v_cndmask_b32_e64 v76, v209, v77, s[42:43]
	v_mov_b32_e32 v160, v187
	v_mov_b32_e32 v161, v77
	v_sub_f32_e32 v246, v188, v186
	v_sub_f32_e32 v78, v188, v76
	v_pk_mul_f32 v[36:37], v[36:37], v[236:237] op_sel_hi:[1,0]
	v_pk_mul_f32 v[32:33], v[32:33], v[0:1] op_sel_hi:[1,0]
	v_pk_mul_f32 v[34:35], v[34:35], v[236:237] op_sel_hi:[1,0]
	v_pk_mul_f32 v[30:31], v[30:31], v[0:1] op_sel_hi:[1,0]
	v_pk_mul_f32 v[48:49], v[48:49], v[236:237] op_sel_hi:[1,0]
	v_pk_mul_f32 v[28:29], v[28:29], v[0:1] op_sel_hi:[1,0]
	v_pk_mul_f32 v[46:47], v[46:47], v[236:237] op_sel_hi:[1,0]
	v_pk_mul_f32 v[26:27], v[26:27], v[0:1] op_sel_hi:[1,0]
	v_pk_mul_f32 v[44:45], v[44:45], v[236:237] op_sel_hi:[1,0]
	v_pk_mul_f32 v[24:25], v[24:25], v[0:1] op_sel_hi:[1,0]
	v_pk_mul_f32 v[42:43], v[42:43], v[236:237] op_sel_hi:[1,0]
	v_pk_mul_f32 v[22:23], v[22:23], v[0:1] op_sel_hi:[1,0]
	v_pk_mul_f32 v[52:53], v[52:53], v[236:237] op_sel_hi:[1,0]
	v_pk_mul_f32 v[20:21], v[20:21], v[0:1] op_sel_hi:[1,0]
	v_pk_mul_f32 v[50:51], v[50:51], v[236:237] op_sel_hi:[1,0]
	v_pk_mul_f32 v[18:19], v[18:19], v[0:1] op_sel_hi:[1,0]
	v_pk_fma_f32 v[170:171], v[170:171], s[36:37], v[246:247] op_sel_hi:[1,0,0]
	v_pk_fma_f32 v[64:65], v[64:65], s[36:37], v[78:79] op_sel_hi:[1,0,0]
	v_pk_fma_f32 v[172:173], v[172:173], s[36:37], v[246:247] op_sel_hi:[1,0,0]
	v_pk_fma_f32 v[66:67], v[66:67], s[36:37], v[78:79] op_sel_hi:[1,0,0]
	v_pk_fma_f32 v[174:175], v[174:175], s[36:37], v[246:247] op_sel_hi:[1,0,0]
	v_pk_fma_f32 v[68:69], v[68:69], s[36:37], v[78:79] op_sel_hi:[1,0,0]
	v_pk_fma_f32 v[176:177], v[176:177], s[36:37], v[246:247] op_sel_hi:[1,0,0]
	v_pk_fma_f32 v[70:71], v[70:71], s[36:37], v[78:79] op_sel_hi:[1,0,0]
	v_pk_fma_f32 v[178:179], v[178:179], s[36:37], v[246:247] op_sel_hi:[1,0,0]
	v_pk_fma_f32 v[72:73], v[72:73], s[36:37], v[78:79] op_sel_hi:[1,0,0]
	v_pk_fma_f32 v[180:181], v[180:181], s[36:37], v[246:247] op_sel_hi:[1,0,0]
	v_pk_fma_f32 v[74:75], v[74:75], s[36:37], v[78:79] op_sel_hi:[1,0,0]
	v_pk_fma_f32 v[182:183], v[182:183], s[36:37], v[246:247] op_sel_hi:[1,0,0]
	v_pk_fma_f32 v[80:81], v[80:81], s[36:37], v[78:79] op_sel_hi:[1,0,0]
	v_pk_fma_f32 v[184:185], v[184:185], s[36:37], v[246:247] op_sel_hi:[1,0,0]
	v_pk_fma_f32 v[82:83], v[82:83], s[36:37], v[78:79] op_sel_hi:[1,0,0]
	v_exp_f32_e32 v170, v170
	v_exp_f32_e32 v64, v64
	v_exp_f32_e32 v171, v171
	v_exp_f32_e32 v65, v65
	v_exp_f32_e32 v172, v172
	v_exp_f32_e32 v66, v66
	v_exp_f32_e32 v173, v173
	v_exp_f32_e32 v67, v67
	v_exp_f32_e32 v174, v174
	v_exp_f32_e32 v68, v68
	v_exp_f32_e32 v175, v175
	v_exp_f32_e32 v69, v69
	v_exp_f32_e32 v176, v176
	v_exp_f32_e32 v70, v70
	v_exp_f32_e32 v177, v177
	v_exp_f32_e32 v71, v71
	v_exp_f32_e32 v178, v178
	v_exp_f32_e32 v72, v72
	v_exp_f32_e32 v179, v179
	v_exp_f32_e32 v73, v73
	v_exp_f32_e32 v180, v180
	v_exp_f32_e32 v74, v74
	v_exp_f32_e32 v181, v181
	v_exp_f32_e32 v75, v75
	v_exp_f32_e32 v182, v182
	v_exp_f32_e32 v80, v80
	v_exp_f32_e32 v183, v183
	v_exp_f32_e32 v81, v81
	v_exp_f32_e32 v184, v184
	v_exp_f32_e32 v82, v82
	v_exp_f32_e32 v185, v185
	v_exp_f32_e32 v83, v83
	v_pk_add_f32 v[238:239], v[170:171], v[172:173]
	v_pk_add_f32 v[84:85], v[64:65], v[66:67]
	v_pk_add_f32 v[240:241], v[174:175], v[176:177]
	v_pk_add_f32 v[86:87], v[68:69], v[70:71]
	v_pk_add_f32 v[242:243], v[178:179], v[180:181]
	v_pk_add_f32 v[76:77], v[72:73], v[74:75]
	v_pk_add_f32 v[244:245], v[182:183], v[184:185]
	v_pk_add_f32 v[78:79], v[80:81], v[82:83]
	v_pk_add_f32 v[238:239], v[238:239], v[240:241]
	v_pk_add_f32 v[84:85], v[84:85], v[86:87]
	v_pk_add_f32 v[242:243], v[242:243], v[244:245]
	v_pk_add_f32 v[76:77], v[76:77], v[78:79]
	v_pk_add_f32 v[238:239], v[238:239], v[242:243]
	v_pk_add_f32 v[84:85], v[84:85], v[76:77]
	v_add_f32_e32 v238, v238, v239
	v_add_f32_e32 v84, v84, v85
	v_fma_f32 v144, v144, v236, v238
	v_fma_f32 v145, v145, v0, v84
	v_cvt_pk_bf16_f32 v58, v170, v171
	v_cvt_pk_bf16_f32 v67, v66, v67
	v_cvt_pk_bf16_f32 v59, v172, v173
	v_cvt_pk_bf16_f32 v66, v64, v65
	v_cvt_pk_bf16_f32 v60, v174, v175
	v_cvt_pk_bf16_f32 v68, v68, v69
	v_cvt_pk_bf16_f32 v61, v176, v177
	v_cvt_pk_bf16_f32 v69, v70, v71
	v_cvt_pk_bf16_f32 v54, v178, v179
	v_cvt_pk_bf16_f32 v62, v72, v73
	v_cvt_pk_bf16_f32 v55, v180, v181
	v_cvt_pk_bf16_f32 v63, v74, v75
	v_cvt_pk_bf16_f32 v56, v182, v183
	v_cvt_pk_bf16_f32 v64, v80, v81
	v_cvt_pk_bf16_f32 v57, v184, v185
	v_cvt_pk_bf16_f32 v65, v82, v83
	s_branch .LBB0_446
.Lp2v_only0:
	v_mfma_f32_16x16x32_bf16 v[170:173], v[64:67], v[2:5], 0
	v_mfma_f32_16x16x32_bf16 v[174:177], v[68:71], v[2:5], 0
	v_mfma_f32_16x16x32_bf16 v[170:173], v[54:57], v[6:9], v[170:173]
	v_mfma_f32_16x16x32_bf16 v[178:181], v[72:75], v[2:5], 0
	v_mfma_f32_16x16x32_bf16 v[174:177], v[58:61], v[6:9], v[174:177]
	v_mfma_f32_16x16x32_bf16 v[182:185], v[80:83], v[2:5], 0
	v_mfma_f32_16x16x32_bf16 v[178:181], v[76:79], v[6:9], v[178:181]
	v_mfma_f32_16x16x32_bf16 v[182:185], v[84:87], v[6:9], v[182:185]
	s_nop 7
	s_nop 7
	v_max3_f32 v186, v170, v171, v172
	v_max3_f32 v186, v186, v173, v174
	v_max3_f32 v186, v186, v175, v176
	v_max3_f32 v186, v186, v177, v178
	v_max3_f32 v186, v186, v179, v180
	v_max3_f32 v186, v186, v181, v182
	v_max3_f32 v186, v186, v183, v184
	v_max_f32_e32 v186, v186, v185
	v_mov_b32_e32 v187, v186
	s_nop 1
	v_permlane16_swap_b32_e32 v186, v187
	v_max_f32_e32 v186, v186, v187
	v_mov_b32_e32 v187, v186
	s_nop 1
	v_permlane32_swap_b32_e32 v186, v187
	v_max_f32_e32 v186, v186, v187
	v_fma_f32 v186, v186, s36, v188
	v_max_f32_e32 v186, s29, v186
	v_cndmask_b32_e64 v186, v148, v186, s[44:45]
	v_max_f32_e32 v187, v160, v186
	v_sub_f32_e32 v248, v160, v187
	v_exp_f32_e32 v236, v248
	v_cndmask_b32_e64 v186, v209, v187, s[44:45]
	v_mov_b32_e32 v160, v187
	v_sub_f32_e32 v246, v188, v186
	v_pk_mul_f32 v[36:37], v[36:37], v[236:237] op_sel_hi:[1,0]
	v_pk_mul_f32 v[34:35], v[34:35], v[236:237] op_sel_hi:[1,0]
	v_pk_mul_f32 v[48:49], v[48:49], v[236:237] op_sel_hi:[1,0]
	v_pk_mul_f32 v[46:47], v[46:47], v[236:237] op_sel_hi:[1,0]
	v_pk_mul_f32 v[44:45], v[44:45], v[236:237] op_sel_hi:[1,0]
	v_pk_mul_f32 v[42:43], v[42:43], v[236:237] op_sel_hi:[1,0]
	v_pk_mul_f32 v[52:53], v[52:53], v[236:237] op_sel_hi:[1,0]
	v_pk_mul_f32 v[50:51], v[50:51], v[236:237] op_sel_hi:[1,0]
	v_pk_fma_f32 v[170:171], v[170:171], s[36:37], v[246:247] op_sel_hi:[1,0,0]
	v_pk_fma_f32 v[172:173], v[172:173], s[36:37], v[246:247] op_sel_hi:[1,0,0]
	v_pk_fma_f32 v[174:175], v[174:175], s[36:37], v[246:247] op_sel_hi:[1,0,0]
	v_pk_fma_f32 v[176:177], v[176:177], s[36:37], v[246:247] op_sel_hi:[1,0,0]
	v_pk_fma_f32 v[178:179], v[178:179], s[36:37], v[246:247] op_sel_hi:[1,0,0]
	v_pk_fma_f32 v[180:181], v[180:181], s[36:37], v[246:247] op_sel_hi:[1,0,0]
	v_pk_fma_f32 v[182:183], v[182:183], s[36:37], v[246:247] op_sel_hi:[1,0,0]
	v_pk_fma_f32 v[184:185], v[184:185], s[36:37], v[246:247] op_sel_hi:[1,0,0]
	v_exp_f32_e32 v170, v170
	v_exp_f32_e32 v171, v171
	v_exp_f32_e32 v172, v172
	v_exp_f32_e32 v173, v173
	v_exp_f32_e32 v174, v174
	v_exp_f32_e32 v175, v175
	v_exp_f32_e32 v176, v176
	v_exp_f32_e32 v177, v177
	v_exp_f32_e32 v178, v178
	v_exp_f32_e32 v179, v179
	v_exp_f32_e32 v180, v180
	v_exp_f32_e32 v181, v181
	v_exp_f32_e32 v182, v182
	v_exp_f32_e32 v183, v183
	v_exp_f32_e32 v184, v184
	v_exp_f32_e32 v185, v185
	s_nop 0
	v_pk_add_f32 v[238:239], v[170:171], v[172:173]
	v_pk_add_f32 v[240:241], v[174:175], v[176:177]
	v_pk_add_f32 v[242:243], v[178:179], v[180:181]
	v_pk_add_f32 v[244:245], v[182:183], v[184:185]
	v_pk_add_f32 v[238:239], v[238:239], v[240:241]
	v_pk_add_f32 v[242:243], v[242:243], v[244:245]
	s_nop 0
	v_pk_add_f32 v[238:239], v[238:239], v[242:243]
	s_nop 0
	v_add_f32_e32 v238, v238, v239
	v_fma_f32 v144, v144, v236, v238
	v_cvt_pk_bf16_f32 v58, v170, v171
	v_cvt_pk_bf16_f32 v59, v172, v173
	v_cvt_pk_bf16_f32 v60, v174, v175
	v_cvt_pk_bf16_f32 v61, v176, v177
	v_cvt_pk_bf16_f32 v54, v178, v179
	v_cvt_pk_bf16_f32 v55, v180, v181
	v_cvt_pk_bf16_f32 v56, v182, v183
	v_cvt_pk_bf16_f32 v57, v184, v185
	s_branch .LBB0_445
.Lp2v_m1:
	v_mfma_f32_16x16x32_bf16 v[64:67], v[64:67], v[10:13], 0
	v_mfma_f32_16x16x32_bf16 v[68:71], v[68:71], v[10:13], 0
	v_mfma_f32_16x16x32_bf16 v[64:67], v[54:57], v[14:17], v[64:67]
	v_mfma_f32_16x16x32_bf16 v[72:75], v[72:75], v[10:13], 0
	v_mfma_f32_16x16x32_bf16 v[68:71], v[58:61], v[14:17], v[68:71]
	v_mfma_f32_16x16x32_bf16 v[80:83], v[80:83], v[10:13], 0
	v_mfma_f32_16x16x32_bf16 v[72:75], v[76:79], v[14:17], v[72:75]
	v_mfma_f32_16x16x32_bf16 v[80:83], v[84:87], v[14:17], v[80:83]
	s_nop 7
	s_nop 7
	v_mov_b32_e32 v54, 0
	v_mov_b32_e32 v55, v54
	v_mov_b32_e32 v56, v54
	v_mov_b32_e32 v57, v54
	v_mov_b32_e32 v58, v54
	v_mov_b32_e32 v59, v54
	v_mov_b32_e32 v60, v54
	v_mov_b32_e32 v61, v54
	v_max3_f32 v76, v64, v65, v66
	v_max3_f32 v76, v76, v67, v68
	v_max3_f32 v76, v76, v69, v70
	v_max3_f32 v76, v76, v71, v72
	v_max3_f32 v76, v76, v73, v74
	v_max3_f32 v76, v76, v75, v80
	v_max3_f32 v76, v76, v81, v82
	v_max_f32_e32 v76, v76, v83
	v_mov_b32_e32 v77, v76
	s_nop 1
	v_permlane16_swap_b32_e32 v76, v77
	v_max_f32_e32 v76, v76, v77
	v_mov_b32_e32 v77, v76
	s_nop 1
	v_permlane32_swap_b32_e32 v76, v77
	v_max_f32_e32 v76, v76, v77
	v_fma_f32 v76, v76, s36, v188
	v_max_f32_e32 v76, s29, v76
	v_cndmask_b32_e64 v76, v148, v76, s[42:43]
	v_max_f32_e32 v77, v161, v76
	v_sub_f32_e32 v0, v161, v77
	v_exp_f32_e32 v0, v0
	v_cndmask_b32_e64 v76, v209, v77, s[42:43]
	v_mov_b32_e32 v161, v77
	v_sub_f32_e32 v78, v188, v76
	v_pk_mul_f32 v[32:33], v[32:33], v[0:1] op_sel_hi:[1,0]
	v_pk_mul_f32 v[30:31], v[30:31], v[0:1] op_sel_hi:[1,0]
	v_pk_mul_f32 v[28:29], v[28:29], v[0:1] op_sel_hi:[1,0]
	v_pk_mul_f32 v[26:27], v[26:27], v[0:1] op_sel_hi:[1,0]
	v_pk_mul_f32 v[24:25], v[24:25], v[0:1] op_sel_hi:[1,0]
	v_pk_mul_f32 v[22:23], v[22:23], v[0:1] op_sel_hi:[1,0]
	v_pk_mul_f32 v[20:21], v[20:21], v[0:1] op_sel_hi:[1,0]
	v_pk_mul_f32 v[18:19], v[18:19], v[0:1] op_sel_hi:[1,0]
	v_pk_fma_f32 v[64:65], v[64:65], s[36:37], v[78:79] op_sel_hi:[1,0,0]
	v_pk_fma_f32 v[66:67], v[66:67], s[36:37], v[78:79] op_sel_hi:[1,0,0]
	v_pk_fma_f32 v[68:69], v[68:69], s[36:37], v[78:79] op_sel_hi:[1,0,0]
	v_pk_fma_f32 v[70:71], v[70:71], s[36:37], v[78:79] op_sel_hi:[1,0,0]
	v_pk_fma_f32 v[72:73], v[72:73], s[36:37], v[78:79] op_sel_hi:[1,0,0]
	v_pk_fma_f32 v[74:75], v[74:75], s[36:37], v[78:79] op_sel_hi:[1,0,0]
	v_pk_fma_f32 v[80:81], v[80:81], s[36:37], v[78:79] op_sel_hi:[1,0,0]
	v_pk_fma_f32 v[82:83], v[82:83], s[36:37], v[78:79] op_sel_hi:[1,0,0]
	v_exp_f32_e32 v64, v64
	v_exp_f32_e32 v65, v65
	v_exp_f32_e32 v66, v66
	v_exp_f32_e32 v67, v67
	v_exp_f32_e32 v68, v68
	v_exp_f32_e32 v69, v69
	v_exp_f32_e32 v70, v70
	v_exp_f32_e32 v71, v71
	v_exp_f32_e32 v72, v72
	v_exp_f32_e32 v73, v73
	v_exp_f32_e32 v74, v74
	v_exp_f32_e32 v75, v75
	v_exp_f32_e32 v80, v80
	v_exp_f32_e32 v81, v81
	v_exp_f32_e32 v82, v82
	v_exp_f32_e32 v83, v83
	s_nop 0
	v_pk_add_f32 v[84:85], v[64:65], v[66:67]
	v_pk_add_f32 v[86:87], v[68:69], v[70:71]
	v_pk_add_f32 v[76:77], v[72:73], v[74:75]
	v_pk_add_f32 v[78:79], v[80:81], v[82:83]
	v_pk_add_f32 v[84:85], v[84:85], v[86:87]
	v_pk_add_f32 v[76:77], v[76:77], v[78:79]
	s_nop 0
	v_pk_add_f32 v[84:85], v[84:85], v[76:77]
	s_nop 0
	v_add_f32_e32 v84, v84, v85
	v_fma_f32 v145, v145, v0, v84
	v_cvt_pk_bf16_f32 v67, v66, v67
	v_cvt_pk_bf16_f32 v66, v64, v65
	v_cvt_pk_bf16_f32 v68, v68, v69
	v_cvt_pk_bf16_f32 v69, v70, v71
	v_cvt_pk_bf16_f32 v62, v72, v73
	v_cvt_pk_bf16_f32 v63, v74, v75
	v_cvt_pk_bf16_f32 v64, v80, v81
	v_cvt_pk_bf16_f32 v65, v82, v83
	s_branch .LBB0_446
